# queue ds hand-off, padded so all later code keeps best2 byte offsets (placement test)
# speedup vs baseline: 1.0055x; 1.0035x over previous
; DI int tid_opaque() { int t = threadIdx.x; asm volatile("" : "+v"(t)); return t; }
; DI float fexp2(float x) { return __builtin_amdgcn_exp2f(x); }
; __device__ void dilc_item(const Params& p, int item) {
;   const int tid = tid_opaque();
;   const int tokg = item * 64 + (tid >> 3), hh = (tid >> 2) & 1, d0 = (tid & 3) * 16;
;   const int b = tokg >> 13, t = tokg & (SEQ - 1);
;   const float* dilo = (const float*)(p.ws + OFF_DILO);
;   const float* dill = (const float*)(p.ws + OFF_DILL);
;   float ls[3]; const float* op[3];
; #pragma unroll
;   for (int g = 0; g < 3; ++g) {
;     int sh = 2 * g;
;     size_t prow = (size_t)(b * 3 + g) * SEQ + (size_t)(t & ((1 << sh) - 1)) * (SEQ >> sh) + (t >> sh);
;     ls[g] = dill[prow * 2 + hh];
;     op[g] = dilo + (prow * 2 + hh) * 64 + d0;
;   }
;   float mx = fmaxf(ls[0], fmaxf(ls[1], ls[2]));
;   float e0 = fexp2(ls[0] - mx), e1 = fexp2(ls[1] - mx), e2 = fexp2(ls[2] - mx);
;   float inv = 1.f / (e0 + e1 + e2);
;   e0 *= inv; e1 *= inv; e2 *= inv;
;   bf16* cat = (bf16*)(p.ws + OFF_CAT) + ((size_t)(4 + hh) * NT + tokg) * 64 + d0;
;   f32x4 va[3][4];
; #pragma unroll
;   for (int g = 0; g < 3; ++g)
; #pragma unroll
;     for (int q = 0; q < 4; ++q) va[g][q] = *(const f32x4*)(op[g] + 4 * q);
;   __builtin_amdgcn_sched_barrier(0);
;   u32x4 o0, o1;
; #pragma unroll
;   for (int q = 0; q < 4; ++q) {
;     const f32x4 a = va[0][q], bb = va[1][q], cc = va[2][q];
;     float v0 = e0 * a[0] + e1 * bb[0] + e2 * cc[0], v1 = e0 * a[1] + e1 * bb[1] + e2 * cc[1];
;     float v2 = e0 * a[2] + e1 * bb[2] + e2 * cc[2], v3 = e0 * a[3] + e1 * bb[3] + e2 * cc[3];
;     if (q < 2) { o0[2 * q] = pack2(v0, v1); o0[2 * q + 1] = pack2(v2, v3); }
;     else { o1[2 * (q - 2)] = pack2(v0, v1); o1[2 * (q - 2) + 1] = pack2(v2, v3); }
;   }
;   *(u32x4*)cat = o0; *(u32x4*)(cat + 8) = o1;
; __global__ void __launch_bounds__(512, 2) fwd_megakernel(Params p) {
;     ...
;       for (;;) {
;         __syncthreads();
;         if (threadIdx.x == 0) *qslot = (int)atomicAdd(qcnt, 1u);
;         __syncthreads();
;         const int q = *qslot;
;         if (q >= qtotal) break;
.LBB0_393:
	s_or_b64 exec, exec, s[0:1]
	s_add_i32 s0, 0, 0x21040
	v_readlane_b32 s2, v254, 40
	s_cmp_lg_u32 s0, -1
	v_readlane_b32 s3, v254, 41
	s_cselect_b32 s0, s0, 0
	s_cselect_b32 s1, s3, 0
	v_mov_b32_e32 v2, s0
	v_mov_b32_e32 v3, s1
	s_waitcnt lgkmcnt(0)
	s_barrier
	ds_read_b32 v0, v2
	v_readlane_b32 s0, v255, 36
	s_waitcnt lgkmcnt(0)
	s_nop 0
	s_nop 0
	s_nop 0
	s_nop 0
	s_nop 0
	s_nop 0
	s_nop 0
	v_cmp_gt_i32_e32 vcc, s0, v0
	s_mov_b64 s[0:1], -1
	s_mov_b64 s[2:3], exec
	v_writelane_b32 v255, s2, 44
	s_nop 1
	v_writelane_b32 v255, s3, 45
	s_and_b64 s[2:3], s[2:3], vcc
	s_mov_b64 exec, s[2:3]
	s_cbranch_execz .LBB0_388
	s_movk_i32 s0, 0x17f
	v_cmp_lt_i32_e32 vcc, s0, v0
	s_and_saveexec_b64 s[0:1], vcc
	s_xor_b64 s[6:7], exec, s[0:1]
	s_cbranch_execz .LBB0_449
	v_readlane_b32 s0, v255, 35
	s_nop 1
	v_cmp_le_i32_e32 vcc, s0, v0
	s_and_saveexec_b64 s[0:1], vcc
	s_xor_b64 s[0:1], exec, s[0:1]
	s_cbranch_execz .LBB0_397
	v_readlane_b32 s2, v255, 37
	v_mov_b32_e32 v2, v228
	s_mov_b64 s[4:5], 0x4000
	v_add_u32_e32 v0, s2, v0
	v_ashrrev_i32_e32 v12, 3, v2
	v_lshl_add_u32 v50, v0, 6, v12
	v_lshlrev_b32_e32 v0, 4, v2
	v_and_b32_e32 v53, 48, v0
	v_ashrrev_i32_e32 v0, 13, v50
	v_bfe_u32 v51, v2, 2, 1
	v_mul_i32_i24_e32 v2, 3, v0
	v_readlane_b32 s2, v254, 48
	v_and_b32_e32 v8, 0x1fff, v50
	v_lshlrev_b32_e32 v0, 2, v53
	v_readlane_b32 s3, v254, 49
	v_ashrrev_i32_e32 v3, 31, v2
	v_lshlrev_b64 v[6:7], 14, v[2:3]
	v_lshl_add_u64 v[4:5], s[2:3], 0, v[0:1]
	v_lshlrev_b32_e32 v0, 1, v8
	v_readlane_b32 s2, v254, 50
	v_or3_b32 v6, v6, v0, v51
	v_readlane_b32 s3, v254, 51
	v_lshlrev_b32_e32 v0, 11, v12
	v_and_b32_e32 v0, 0x1800, v0
	v_lshl_add_u64 v[8:9], v[6:7], 2, s[2:3]
	v_lshlrev_b64 v[6:7], 8, v[6:7]
	v_lshl_add_u64 v[14:15], v[4:5], 0, v[6:7]
	v_bfe_u32 v6, v50, 2, 11
	v_lshlrev_b64 v[2:3], 13, v[2:3]
	v_or3_b32 v6, v2, v6, v0
	v_mov_b32_e32 v7, v3
	v_lshlrev_b64 v[6:7], 1, v[6:7]
	v_or_b32_e32 v6, v6, v51
	v_lshl_add_u64 v[6:7], v[6:7], 0, s[4:5]
	v_lshl_add_u64 v[10:11], v[6:7], 2, s[2:3]
	v_lshlrev_b64 v[6:7], 8, v[6:7]
	v_lshlrev_b32_e32 v0, 9, v12
	v_lshl_add_u64 v[30:31], v[4:5], 0, v[6:7]
	v_and_b32_e32 v0, 0x1e00, v0
	v_bfe_u32 v6, v50, 4, 9
	v_or3_b32 v2, v2, v6, v0
	v_lshlrev_b64 v[2:3], 1, v[2:3]
	v_or_b32_e32 v2, v2, v51
	s_mov_b64 s[4:5], 0x8000
	v_lshl_add_u64 v[2:3], v[2:3], 0, s[4:5]
	v_lshl_add_u64 v[34:35], v[2:3], 2, s[2:3]
	v_lshlrev_b64 v[2:3], 8, v[2:3]
	v_lshl_add_u64 v[46:47], v[4:5], 0, v[2:3]
	global_load_dword v0, v[8:9], off
	global_load_dwordx4 v[2:5], v[14:15], off
	global_load_dword v52, v[10:11], off
	s_nop 0
	global_load_dwordx4 v[6:9], v[14:15], off offset:48
	global_load_dwordx4 v[10:13], v[14:15], off offset:16
	s_nop 0
	global_load_dwordx4 v[14:17], v[14:15], off offset:32
	s_nop 0
	global_load_dwordx4 v[18:21], v[30:31], off offset:16
	global_load_dwordx4 v[22:25], v[30:31], off
	global_load_dwordx4 v[26:29], v[30:31], off offset:48
	s_nop 0
	global_load_dwordx4 v[30:33], v[30:31], off offset:32
	s_nop 0
	global_load_dword v54, v[34:35], off
	s_nop 0
	global_load_dwordx4 v[34:37], v[46:47], off
	global_load_dwordx4 v[38:41], v[46:47], off offset:48
	global_load_dwordx4 v[42:45], v[46:47], off offset:16
	s_nop 0
	global_load_dwordx4 v[46:49], v[46:47], off offset:32
	s_waitcnt vmcnt(4)
	v_max3_f32 v55, v0, v52, v54
	v_sub_f32_e32 v0, v0, v55
	v_sub_f32_e32 v52, v52, v55
	v_exp_f32_e32 v0, v0
	v_sub_f32_e32 v54, v54, v55
	v_exp_f32_e32 v52, v52
	v_exp_f32_e32 v54, v54
	v_add_f32_e32 v55, v0, v52
	v_add_f32_e32 v55, v54, v55
	v_div_scale_f32 v56, s[2:3], v55, v55, 1.0
	v_rcp_f32_e32 v57, v56
	v_readlane_b32 s2, v254, 58
	v_readlane_b32 s3, v254, 59
	v_fma_f32 v58, -v56, v57, 1.0
	v_fmac_f32_e32 v57, v58, v57
	v_div_scale_f32 v58, vcc, 1.0, v55, 1.0
	v_mul_f32_e32 v59, v58, v57
	v_fma_f32 v60, -v56, v59, v58
	v_fmac_f32_e32 v59, v60, v57
	v_fma_f32 v56, -v56, v59, v58
	v_div_fmas_f32 v56, v56, v57, v59
	v_div_fixup_f32 v55, v56, v55, 1.0
	v_mul_f32_e32 v52, v52, v55
	v_mul_f32_e32 v0, v0, v55
	v_pk_mul_f32 v[30:31], v[52:53], v[30:31] op_sel_hi:[0,1]
	v_pk_fma_f32 v[14:15], v[14:15], v[0:1], v[30:31] op_sel_hi:[1,0,1]
	v_pk_mul_f32 v[30:31], v[52:53], v[32:33] op_sel_hi:[0,1]
	v_mul_f32_e32 v54, v54, v55
	v_pk_fma_f32 v[16:17], v[16:17], v[0:1], v[30:31] op_sel_hi:[1,0,1]
	s_waitcnt vmcnt(0)
	v_pk_fma_f32 v[14:15], v[54:55], v[46:47], v[14:15] op_sel_hi:[0,1,1]
	v_pk_fma_f32 v[16:17], v[54:55], v[48:49], v[16:17] op_sel_hi:[0,1,1]
	v_cvt_pk_bf16_f32 v14, v14, v15
	v_cvt_pk_bf16_f32 v15, v16, v17
	v_pk_mul_f32 v[16:17], v[52:53], v[26:27] op_sel_hi:[0,1]
	v_pk_fma_f32 v[6:7], v[6:7], v[0:1], v[16:17] op_sel_hi:[1,0,1]
	s_nop 0
	v_pk_fma_f32 v[6:7], v[54:55], v[38:39], v[6:7] op_sel_hi:[0,1,1]
	v_cvt_pk_bf16_f32 v16, v6, v7
	v_pk_mul_f32 v[6:7], v[52:53], v[28:29] op_sel_hi:[0,1]
	v_pk_fma_f32 v[6:7], v[8:9], v[0:1], v[6:7] op_sel_hi:[1,0,1]
	s_nop 0
	v_pk_fma_f32 v[6:7], v[54:55], v[40:41], v[6:7] op_sel_hi:[0,1,1]
	v_cvt_pk_bf16_f32 v17, v6, v7
	v_pk_mul_f32 v[6:7], v[22:23], v[52:53] op_sel_hi:[1,0]
	s_nop 0
	v_pk_fma_f32 v[2:3], v[2:3], v[0:1], v[6:7] op_sel_hi:[1,0,1]
	v_pk_mul_f32 v[6:7], v[24:25], v[52:53] op_sel_hi:[1,0]
	v_pk_fma_f32 v[2:3], v[54:55], v[34:35], v[2:3] op_sel_hi:[0,1,1]
	v_pk_fma_f32 v[4:5], v[4:5], v[0:1], v[6:7] op_sel_hi:[1,0,1]
	v_cvt_pk_bf16_f32 v2, v2, v3
	v_pk_fma_f32 v[4:5], v[54:55], v[36:37], v[4:5] op_sel_hi:[0,1,1]
	v_cvt_pk_bf16_f32 v3, v4, v5
	v_pk_mul_f32 v[4:5], v[18:19], v[52:53] op_sel_hi:[1,0]
	v_pk_mul_f32 v[6:7], v[20:21], v[52:53] op_sel_hi:[1,0]
	v_pk_fma_f32 v[4:5], v[10:11], v[0:1], v[4:5] op_sel_hi:[1,0,1]
	v_pk_fma_f32 v[6:7], v[12:13], v[0:1], v[6:7] op_sel_hi:[1,0,1]
	v_mov_b32_e32 v0, 0x10000
	v_pk_fma_f32 v[4:5], v[54:55], v[42:43], v[4:5] op_sel_hi:[0,1,1]
	v_pk_fma_f32 v[6:7], v[54:55], v[44:45], v[6:7] op_sel_hi:[0,1,1]
	v_lshl_or_b32 v0, v51, 14, v0
	v_ashrrev_i32_e32 v51, 31, v50
	v_cvt_pk_bf16_f32 v4, v4, v5
	v_cvt_pk_bf16_f32 v5, v6, v7
	v_lshl_add_u64 v[6:7], v[0:1], 0, v[50:51]
	v_lshlrev_b64 v[6:7], 7, v[6:7]
	v_lshl_add_u64 v[6:7], s[2:3], 0, v[6:7]
	v_lshlrev_b32_e32 v0, 1, v53
	v_lshl_add_u64 v[6:7], v[6:7], 0, v[0:1]
	global_store_dwordx4 v[6:7], v[2:5], off
	global_store_dwordx4 v[6:7], v[14:17], off offset:16
